# phase P+1: second-round kvt tiles rotated to workgroups 104-255 (28 instead of 132 workgroups carry a 7th tile); plus ml_state state-update LDS reads pipelined
# speedup vs baseline: 1.0061x; 1.0013x over previous
.LBB0_349:
	s_add_i32 s44, s44, 1
	v_readlane_b32 s2, v252, 63
	s_mul_i32 s2, s44, s2
	s_mul_hi_u32 s3, s44, s33
	s_add_i32 s3, s3, s2
	s_mul_i32 s2, s44, s33
	v_readlane_b32 s13, v253, 14
	s_add_u32 s16, s2, s13
	v_readlane_b32 s2, v252, 62
	s_addc_u32 s17, s3, s2
	s_cmp_eq_u32 s33, 0x100
	s_cbranch_scc0 .Lrot_kvt_done
	s_cmp_lt_u32 s13, 104
	s_cselect_b32 s2, 0x100000, 0
	s_add_u32 s16, s16, s2
	s_addc_u32 s17, s17, 0
	s_sub_u32 s16, s16, 104
	s_subb_u32 s17, s17, 0
.Lrot_kvt_done:
	v_cmp_gt_i64_e32 vcc, s[16:17], v[166:167]
	v_cmp_lt_i64_e64 s[2:3], s[16:17], v[164:165]
	s_cbranch_vccnz .LBB0_351
	s_ashr_i32 s12, s16, 31
	s_lshr_b32 s12, s12, 29
	s_add_i32 s12, s16, s12
	s_ashr_i32 s13, s12, 3
	s_and_b32 s12, s12, -8
	s_sub_i32 s12, s16, s12
	s_cmp_lt_i32 s12, 0
	s_cselect_b32 s14, 52, 51
	s_mul_i32 s12, s12, s14
	s_add_i32 s12, s12, s13
	s_mul_hi_i32 s13, s12, 0x78787879
	s_lshr_b32 s14, s13, 31
	s_ashr_i32 s13, s13, 8
	s_add_i32 s13, s13, s14
	s_lshl_b32 s14, s13, 3
	s_sub_i32 s15, 6, s14
	s_min_i32 s15, s15, 8
	s_abs_i32 s16, s15
	v_cvt_f32_u32_e32 v0, s16
	s_sub_i32 s18, 0, s16
	s_mulk_i32 s13, 0x220
	s_sub_i32 s13, s12, s13
	v_rcp_iflag_f32_e32 v0, v0
	s_abs_i32 s12, s13
	s_xor_b32 s17, s13, s15
	s_ashr_i32 s17, s17, 31
	v_mul_f32_e32 v0, 0x4f7ffffe, v0
	v_cvt_u32_f32_e32 v0, v0
	s_nop 0
	v_readfirstlane_b32 s19, v0
	s_mul_i32 s18, s18, s19
	s_mul_hi_u32 s18, s19, s18
	s_add_i32 s19, s19, s18
	s_mul_hi_u32 s18, s12, s19
	s_mul_i32 s19, s18, s16
	s_sub_i32 s12, s12, s19
	s_add_i32 s34, s18, 1
	s_sub_i32 s19, s12, s16
	s_cmp_ge_u32 s12, s16
	s_cselect_b32 s18, s34, s18
	s_cselect_b32 s12, s19, s12
	s_add_i32 s19, s18, 1
	s_cmp_ge_u32 s12, s16
	s_cselect_b32 s12, s19, s18
	s_xor_b32 s12, s12, s17
	s_sub_i32 s12, s12, s17
	s_mul_i32 s15, s12, s15
	s_sub_i32 s13, s13, s15
	s_add_i32 s14, s14, s13
